# phase-8 (up-proj, LN-fold + relu^2) epilogue rewritten by hand: 4 f32 VALU per element (fma,fma,max,mul), LDS column/row constants read once; 1350 -> 636 lines
# speedup vs baseline: 1.0061x; 1.0030x over previous
; __device__ __forceinline__ float bf_lo(unsigned w) { return __uint_as_float(w << 16); }
; __device__ __forceinline__ float bf_hi(unsigned w) { return __uint_as_float(w & 0xffff0000u); }
; __device__ __forceinline__ u32x4 pack8(const f32x4 a, const f32x4 b) { u32x4 w; w.x = cvt_pk_bf16(a[0], a[1]); w.y = cvt_pk_bf16(a[2], a[3]); w.z = cvt_pk_bf16(b[0], b[1]); w.w = cvt_pk_bf16(b[2], b[3]); return w; }
;     __device__ __forceinline__ void operator()(const f32x4 (&acc)[2][2][4][2], const pg8::Unit& u, int wr, int wc, int fr, int fq, LAS unsigned char* lds, int par) const {
;     ...
;         const int row0 = u.pm * 256 + wr * 64 + fr, c0 = u.pn * 256 + wc * 64 + 16 * fq;
; #pragma unroll
;         for (int ai = 0; ai < 2; ++ai)
; #pragma unroll
;             for (int m = 0; m < 4; ++m) {
;                 const int row = row0 + ai * 128 + m * 16, lrow = ai * 128 + wr * 64 + m * 16 + fr;
;                 float mu = 0.f, rstd = 1.f; if (fold) { mu = rsb[2 * lrow]; rstd = rsb[2 * lrow + 1]; }
; #pragma unroll
;                 for (int bj = 0; bj < 2; ++bj) {
;                     const size_t off = (size_t)row * ld + c0 + bj * 8;
;                     f32x4 v0 = acc[ai][bj][m][0], v1 = acc[ai][bj][m][1];
;                     if (fold) fold_apply(v0, v1, mu, rstd, cvb, wc * 64 + 16 * fq + bj * 8);
;                     if (MODE == 0) { v0 *= scale; v1 *= scale; }
;                     if (MODE == 1) {
; #pragma unroll
;                         for (int j = 0; j < 4; ++j) { const float a = fmaxf(v0[j], 0.f), b = fmaxf(v1[j], 0.f); v0[j] = a * a; v1[j] = b * b; }
;                     }
;                     if (MODE == 2 || MODE == 3) {
;                         const u32x4 gw = *(const u32x4*)(gate + off);
;                         v0[0] *= bf_lo(gw.x); v0[1] *= bf_hi(gw.x); v0[2] *= bf_lo(gw.y); v0[3] *= bf_hi(gw.y);
;                         v1[0] *= bf_lo(gw.z); v1[1] *= bf_hi(gw.z); v1[2] *= bf_lo(gw.w); v1[3] *= bf_hi(gw.w);
;                     }
;                     if (MODE == 3) {
;                         const u32x4 pw = *(const u32x4*)(o + off);
;                         v0[0] += bf_lo(pw.x); v0[1] += bf_hi(pw.x); v0[2] += bf_lo(pw.y); v0[3] += bf_hi(pw.y);
;                         v1[0] += bf_lo(pw.z); v1[1] += bf_hi(pw.z); v1[2] += bf_lo(pw.w); v1[3] += bf_hi(pw.w);
;                     }
;                     *(u32x4*)(o + off) = pack8(v0, v1);
.LBB0_176:
	s_and_b32 s15, s41, 1
	v_lshl_add_u32 v156, s15, 12, v153
	v_lshl_add_u32 v157, s15, 11, v152
	v_readlane_b32 s26, v251, 43
	v_readlane_b32 s27, v251, 44
	ds_read_b128 v[212:215], v156
	ds_read_b128 v[216:219], v156 offset:16
	ds_read_b128 v[220:223], v156 offset:32
	ds_read_b128 v[224:227], v156 offset:48
	ds_read_b128 v[228:231], v156 offset:64
	ds_read_b128 v[232:235], v156 offset:80
	ds_read_b128 v[236:239], v156 offset:96
	ds_read_b128 v[240:243], v156 offset:112
	ds_read_b64 v[172:173], v157
	ds_read_b64 v[174:175], v157 offset:128
	ds_read_b64 v[176:177], v157 offset:256
	ds_read_b64 v[178:179], v157 offset:384
	ds_read_b64 v[180:181], v157 offset:1024
	ds_read_b64 v[182:183], v157 offset:1152
	ds_read_b64 v[184:185], v157 offset:1280
	ds_read_b64 v[186:187], v157 offset:1408
	v_lshl_add_u32 v158, s24, 8, v148
	v_lshl_or_b32 v159, s40, 8, v150
	v_lshlrev_b32_e32 v201, 14, v158
	v_lshl_add_u32 v201, v159, 1, v201
	s_waitcnt lgkmcnt(0)
	v_mul_f32_e32 v200, v173, v172
	v_mov_b32_e32 v155, v201
	v_fma_f32 v188, -v200, v212, v213
	v_fma_f32 v189, -v200, v214, v215
	v_fma_f32 v190, -v200, v216, v217
	v_fma_f32 v191, -v200, v218, v219
	v_fma_f32 v192, -v200, v220, v221
	v_fma_f32 v193, -v200, v222, v223
	v_fma_f32 v194, -v200, v224, v225
	v_fma_f32 v195, -v200, v226, v227
	v_fma_f32 v126, v173, v126, v188
	v_fma_f32 v127, v173, v127, v189
	v_fma_f32 v128, v173, v128, v190
	v_fma_f32 v129, v173, v129, v191
	v_fma_f32 v122, v173, v122, v192
	v_fma_f32 v123, v173, v123, v193
	v_fma_f32 v124, v173, v124, v194
	v_fma_f32 v125, v173, v125, v195
	v_max_f32_e32 v126, 0, v126
	v_max_f32_e32 v127, 0, v127
	v_max_f32_e32 v128, 0, v128
	v_max_f32_e32 v129, 0, v129
	v_max_f32_e32 v122, 0, v122
	v_max_f32_e32 v123, 0, v123
	v_max_f32_e32 v124, 0, v124
	v_max_f32_e32 v125, 0, v125
	v_mul_f32_e32 v126, v126, v126
	v_mul_f32_e32 v127, v127, v127
	v_mul_f32_e32 v128, v128, v128
	v_mul_f32_e32 v129, v129, v129
	v_mul_f32_e32 v122, v122, v122
	v_mul_f32_e32 v123, v123, v123
	v_mul_f32_e32 v124, v124, v124
	v_mul_f32_e32 v125, v125, v125
	v_cvt_pk_bf16_f32 v196, v126, v127
	v_cvt_pk_bf16_f32 v197, v128, v129
	v_cvt_pk_bf16_f32 v198, v122, v123
	v_cvt_pk_bf16_f32 v199, v124, v125
	global_store_dwordx4 v155, v[196:199], s[26:27]
	v_fma_f32 v188, -v200, v228, v229
	v_fma_f32 v189, -v200, v230, v231
	v_fma_f32 v190, -v200, v232, v233
	v_fma_f32 v191, -v200, v234, v235
	v_fma_f32 v192, -v200, v236, v237
	v_fma_f32 v193, -v200, v238, v239
	v_fma_f32 v194, -v200, v240, v241
	v_fma_f32 v195, -v200, v242, v243
	v_fma_f32 v118, v173, v118, v188
	v_fma_f32 v119, v173, v119, v189
	v_fma_f32 v120, v173, v120, v190
	v_fma_f32 v121, v173, v121, v191
	v_fma_f32 v114, v173, v114, v192
	v_fma_f32 v115, v173, v115, v193
	v_fma_f32 v116, v173, v116, v194
	v_fma_f32 v117, v173, v117, v195
	v_max_f32_e32 v118, 0, v118
	v_max_f32_e32 v119, 0, v119
	v_max_f32_e32 v120, 0, v120
	v_max_f32_e32 v121, 0, v121
	v_max_f32_e32 v114, 0, v114
	v_max_f32_e32 v115, 0, v115
	v_max_f32_e32 v116, 0, v116
	v_max_f32_e32 v117, 0, v117
	v_mul_f32_e32 v118, v118, v118
	v_mul_f32_e32 v119, v119, v119
	v_mul_f32_e32 v120, v120, v120
	v_mul_f32_e32 v121, v121, v121
	v_mul_f32_e32 v114, v114, v114
	v_mul_f32_e32 v115, v115, v115
	v_mul_f32_e32 v116, v116, v116
	v_mul_f32_e32 v117, v117, v117
	v_cvt_pk_bf16_f32 v196, v118, v119
	v_cvt_pk_bf16_f32 v197, v120, v121
	v_cvt_pk_bf16_f32 v198, v114, v115
	v_cvt_pk_bf16_f32 v199, v116, v117
	global_store_dwordx4 v155, v[196:199], s[26:27] offset:16
	v_mul_f32_e32 v200, v175, v174
	v_add_u32_e32 v155, 0x40000, v201
	v_fma_f32 v188, -v200, v212, v213
	v_fma_f32 v189, -v200, v214, v215
	v_fma_f32 v190, -v200, v216, v217
	v_fma_f32 v191, -v200, v218, v219
	v_fma_f32 v192, -v200, v220, v221
	v_fma_f32 v193, -v200, v222, v223
	v_fma_f32 v194, -v200, v224, v225
	v_fma_f32 v195, -v200, v226, v227
	v_fma_f32 v110, v175, v110, v188
	v_fma_f32 v111, v175, v111, v189
	v_fma_f32 v112, v175, v112, v190
	v_fma_f32 v113, v175, v113, v191
	v_fma_f32 v106, v175, v106, v192
	v_fma_f32 v107, v175, v107, v193
	v_fma_f32 v108, v175, v108, v194
	v_fma_f32 v109, v175, v109, v195
	v_max_f32_e32 v110, 0, v110
	v_max_f32_e32 v111, 0, v111
	v_max_f32_e32 v112, 0, v112
	v_max_f32_e32 v113, 0, v113
	v_max_f32_e32 v106, 0, v106
	v_max_f32_e32 v107, 0, v107
	v_max_f32_e32 v108, 0, v108
	v_max_f32_e32 v109, 0, v109
	v_mul_f32_e32 v110, v110, v110
	v_mul_f32_e32 v111, v111, v111
	v_mul_f32_e32 v112, v112, v112
	v_mul_f32_e32 v113, v113, v113
	v_mul_f32_e32 v106, v106, v106
	v_mul_f32_e32 v107, v107, v107
	v_mul_f32_e32 v108, v108, v108
	v_mul_f32_e32 v109, v109, v109
	v_cvt_pk_bf16_f32 v196, v110, v111
	v_cvt_pk_bf16_f32 v197, v112, v113
	v_cvt_pk_bf16_f32 v198, v106, v107
	v_cvt_pk_bf16_f32 v199, v108, v109
	global_store_dwordx4 v155, v[196:199], s[26:27]
	v_fma_f32 v188, -v200, v228, v229
	v_fma_f32 v189, -v200, v230, v231
	v_fma_f32 v190, -v200, v232, v233
	v_fma_f32 v191, -v200, v234, v235
	v_fma_f32 v192, -v200, v236, v237
	v_fma_f32 v193, -v200, v238, v239
	v_fma_f32 v194, -v200, v240, v241
	v_fma_f32 v195, -v200, v242, v243
	v_fma_f32 v102, v175, v102, v188
	v_fma_f32 v103, v175, v103, v189
	v_fma_f32 v104, v175, v104, v190
	v_fma_f32 v105, v175, v105, v191
	v_fma_f32 v98, v175, v98, v192
	v_fma_f32 v99, v175, v99, v193
	v_fma_f32 v100, v175, v100, v194
	v_fma_f32 v101, v175, v101, v195
	v_max_f32_e32 v102, 0, v102
	v_max_f32_e32 v103, 0, v103
	v_max_f32_e32 v104, 0, v104
	v_max_f32_e32 v105, 0, v105
	v_max_f32_e32 v98, 0, v98
	v_max_f32_e32 v99, 0, v99
	v_max_f32_e32 v100, 0, v100
	v_max_f32_e32 v101, 0, v101
	v_mul_f32_e32 v102, v102, v102
	v_mul_f32_e32 v103, v103, v103
; #define LAS __attribute__((address_space(3)))
; __device__ __forceinline__ float bf_lo(unsigned w) { return __uint_as_float(w << 16); }
;     __device__ __forceinline__ void operator()(const f32x4 (&acc)[2][2][4][2], const pg8::Unit& u, int wr, int wc, int fr, int fq, LAS unsigned char* lds, int par) const {
;         const bool fold = F.stats != nullptr;
;         const LAS float* rsb = (const LAS float*)(lds + RS_OFF) + par * 512; const LAS float* cvb = (const LAS float*)(lds + CV_OFF) + (par * 2 + wr) * 512;
;         const int row0 = u.pm * 256 + wr * 64 + fr, c0 = u.pn * 256 + wc * 64 + 16 * fq;
; #pragma unroll
;         for (int ai = 0; ai < 2; ++ai)
; #pragma unroll
;             for (int m = 0; m < 4; ++m) {
;                 const int row = row0 + ai * 128 + m * 16, lrow = ai * 128 + wr * 64 + m * 16 + fr;
;                 float mu = 0.f, rstd = 1.f; if (fold) { mu = rsb[2 * lrow]; rstd = rsb[2 * lrow + 1]; }
; #pragma unroll
;                 for (int bj = 0; bj < 2; ++bj) {
;                     const size_t off = (size_t)row * ld + c0 + bj * 8;
;                     f32x4 v0 = acc[ai][bj][m][0], v1 = acc[ai][bj][m][1];
;                     if (fold) fold_apply(v0, v1, mu, rstd, cvb, wc * 64 + 16 * fq + bj * 8);
;                     if (MODE == 0) { v0 *= scale; v1 *= scale; }
;                     if (MODE == 1) {
; #pragma unroll
;                         for (int j = 0; j < 4; ++j) { const float a = fmaxf(v0[j], 0.f), b = fmaxf(v1[j], 0.f); v0[j] = a * a; v1[j] = b * b; }
;                     }
;                     if (MODE == 2 || MODE == 3) {
;                         const u32x4 gw = *(const u32x4*)(gate + off);
;                         v0[0] *= bf_lo(gw.x); v0[1] *= bf_hi(gw.x); v0[2] *= bf_lo(gw.y); v0[3] *= bf_hi(gw.y);
;                         v1[0] *= bf_lo(gw.z); v1[1] *= bf_hi(gw.z); v1[2] *= bf_lo(gw.w); v1[3] *= bf_hi(gw.w);
;                     }
;                     if (MODE == 3) {
;                         const u32x4 pw = *(const u32x4*)(o + off);
;                         v0[0] += bf_lo(pw.x); v0[1] += bf_hi(pw.x); v0[2] += bf_lo(pw.y); v0[3] += bf_hi(pw.y);
;                         v1[0] += bf_lo(pw.z); v1[1] += bf_hi(pw.z); v1[2] += bf_lo(pw.w); v1[3] += bf_hi(pw.w);
;                     }
;                     *(u32x4*)(o + off) = pack8(v0, v1);
;                 }
	v_mul_f32_e32 v104, v104, v104
	v_mul_f32_e32 v105, v105, v105
	v_mul_f32_e32 v98, v98, v98
	v_mul_f32_e32 v99, v99, v99
	v_mul_f32_e32 v100, v100, v100
	v_mul_f32_e32 v101, v101, v101
	v_cvt_pk_bf16_f32 v196, v102, v103
	v_cvt_pk_bf16_f32 v197, v104, v105
	v_cvt_pk_bf16_f32 v198, v98, v99
	v_cvt_pk_bf16_f32 v199, v100, v101
	global_store_dwordx4 v155, v[196:199], s[26:27] offset:16
	v_mul_f32_e32 v200, v177, v176
	v_add_u32_e32 v155, 0x80000, v201
	v_fma_f32 v188, -v200, v212, v213
	v_fma_f32 v189, -v200, v214, v215
	v_fma_f32 v190, -v200, v216, v217
	v_fma_f32 v191, -v200, v218, v219
	v_fma_f32 v192, -v200, v220, v221
	v_fma_f32 v193, -v200, v222, v223
	v_fma_f32 v194, -v200, v224, v225
	v_fma_f32 v195, -v200, v226, v227
	v_fma_f32 v94, v177, v94, v188
	v_fma_f32 v95, v177, v95, v189
	v_fma_f32 v96, v177, v96, v190
	v_fma_f32 v97, v177, v97, v191
	v_fma_f32 v90, v177, v90, v192
	v_fma_f32 v91, v177, v91, v193
	v_fma_f32 v92, v177, v92, v194
	v_fma_f32 v93, v177, v93, v195
	v_max_f32_e32 v94, 0, v94
	v_max_f32_e32 v95, 0, v95
	v_max_f32_e32 v96, 0, v96
	v_max_f32_e32 v97, 0, v97
	v_max_f32_e32 v90, 0, v90
	v_max_f32_e32 v91, 0, v91
	v_max_f32_e32 v92, 0, v92
	v_max_f32_e32 v93, 0, v93
	v_mul_f32_e32 v94, v94, v94
	v_mul_f32_e32 v95, v95, v95
	v_mul_f32_e32 v96, v96, v96
	v_mul_f32_e32 v97, v97, v97
	v_mul_f32_e32 v90, v90, v90
	v_mul_f32_e32 v91, v91, v91
	v_mul_f32_e32 v92, v92, v92
	v_mul_f32_e32 v93, v93, v93
	v_cvt_pk_bf16_f32 v196, v94, v95
	v_cvt_pk_bf16_f32 v197, v96, v97
	v_cvt_pk_bf16_f32 v198, v90, v91
	v_cvt_pk_bf16_f32 v199, v92, v93
	global_store_dwordx4 v155, v[196:199], s[26:27]
	v_fma_f32 v188, -v200, v228, v229
	v_fma_f32 v189, -v200, v230, v231
	v_fma_f32 v190, -v200, v232, v233
	v_fma_f32 v191, -v200, v234, v235
	v_fma_f32 v192, -v200, v236, v237
	v_fma_f32 v193, -v200, v238, v239
	v_fma_f32 v194, -v200, v240, v241
	v_fma_f32 v195, -v200, v242, v243
	v_fma_f32 v86, v177, v86, v188
	v_fma_f32 v87, v177, v87, v189
	v_fma_f32 v88, v177, v88, v190
	v_fma_f32 v89, v177, v89, v191
	v_fma_f32 v82, v177, v82, v192
	v_fma_f32 v83, v177, v83, v193
	v_fma_f32 v84, v177, v84, v194
	v_fma_f32 v85, v177, v85, v195
	v_max_f32_e32 v86, 0, v86
	v_max_f32_e32 v87, 0, v87
	v_max_f32_e32 v88, 0, v88
	v_max_f32_e32 v89, 0, v89
	v_max_f32_e32 v82, 0, v82
	v_max_f32_e32 v83, 0, v83
	v_max_f32_e32 v84, 0, v84
	v_max_f32_e32 v85, 0, v85
	v_mul_f32_e32 v86, v86, v86
	v_mul_f32_e32 v87, v87, v87
	v_mul_f32_e32 v88, v88, v88
	v_mul_f32_e32 v89, v89, v89
	v_mul_f32_e32 v82, v82, v82
	v_mul_f32_e32 v83, v83, v83
	v_mul_f32_e32 v84, v84, v84
	v_mul_f32_e32 v85, v85, v85
	v_cvt_pk_bf16_f32 v196, v86, v87
	v_cvt_pk_bf16_f32 v197, v88, v89
	v_cvt_pk_bf16_f32 v198, v82, v83
	v_cvt_pk_bf16_f32 v199, v84, v85
	global_store_dwordx4 v155, v[196:199], s[26:27] offset:16
	v_mul_f32_e32 v200, v179, v178
	v_add_u32_e32 v155, 0xc0000, v201
	v_fma_f32 v188, -v200, v212, v213
	v_fma_f32 v189, -v200, v214, v215
	v_fma_f32 v190, -v200, v216, v217
	v_fma_f32 v191, -v200, v218, v219
	v_fma_f32 v192, -v200, v220, v221
	v_fma_f32 v193, -v200, v222, v223
	v_fma_f32 v194, -v200, v224, v225
	v_fma_f32 v195, -v200, v226, v227
	v_fma_f32 v78, v179, v78, v188
	v_fma_f32 v79, v179, v79, v189
	v_fma_f32 v80, v179, v80, v190
	v_fma_f32 v81, v179, v81, v191
	v_fma_f32 v74, v179, v74, v192
	v_fma_f32 v75, v179, v75, v193
	v_fma_f32 v76, v179, v76, v194
	v_fma_f32 v77, v179, v77, v195
	v_max_f32_e32 v78, 0, v78
	v_max_f32_e32 v79, 0, v79
	v_max_f32_e32 v80, 0, v80
	v_max_f32_e32 v81, 0, v81
	v_max_f32_e32 v74, 0, v74
	v_max_f32_e32 v75, 0, v75
	v_max_f32_e32 v76, 0, v76
	v_max_f32_e32 v77, 0, v77
	v_mul_f32_e32 v78, v78, v78
	v_mul_f32_e32 v79, v79, v79
	v_mul_f32_e32 v80, v80, v80
	v_mul_f32_e32 v81, v81, v81
	v_mul_f32_e32 v74, v74, v74
	v_mul_f32_e32 v75, v75, v75
	v_mul_f32_e32 v76, v76, v76
	v_mul_f32_e32 v77, v77, v77
	v_cvt_pk_bf16_f32 v196, v78, v79
	v_cvt_pk_bf16_f32 v197, v80, v81
	v_cvt_pk_bf16_f32 v198, v74, v75
	v_cvt_pk_bf16_f32 v199, v76, v77
	global_store_dwordx4 v155, v[196:199], s[26:27]
	v_fma_f32 v188, -v200, v228, v229
	v_fma_f32 v189, -v200, v230, v231
	v_fma_f32 v190, -v200, v232, v233
	v_fma_f32 v191, -v200, v234, v235
	v_fma_f32 v192, -v200, v236, v237
	v_fma_f32 v193, -v200, v238, v239
	v_fma_f32 v194, -v200, v240, v241
	v_fma_f32 v195, -v200, v242, v243
	v_fma_f32 v70, v179, v70, v188
	v_fma_f32 v71, v179, v71, v189
	v_fma_f32 v72, v179, v72, v190
	v_fma_f32 v73, v179, v73, v191
	v_fma_f32 v66, v179, v66, v192
	v_fma_f32 v67, v179, v67, v193
	v_fma_f32 v68, v179, v68, v194
	v_fma_f32 v69, v179, v69, v195
	v_max_f32_e32 v70, 0, v70
	v_max_f32_e32 v71, 0, v71
	v_max_f32_e32 v72, 0, v72
	v_max_f32_e32 v73, 0, v73
	v_max_f32_e32 v66, 0, v66
	v_max_f32_e32 v67, 0, v67
	v_max_f32_e32 v68, 0, v68
	v_max_f32_e32 v69, 0, v69
	v_mul_f32_e32 v70, v70, v70
	v_mul_f32_e32 v71, v71, v71
	v_mul_f32_e32 v72, v72, v72
	v_mul_f32_e32 v73, v73, v73
	v_mul_f32_e32 v66, v66, v66
	v_mul_f32_e32 v67, v67, v67
	v_mul_f32_e32 v68, v68, v68
	v_mul_f32_e32 v69, v69, v69
	v_cvt_pk_bf16_f32 v196, v70, v71
	v_cvt_pk_bf16_f32 v197, v72, v73
	v_cvt_pk_bf16_f32 v198, v66, v67
	v_cvt_pk_bf16_f32 v199, v68, v69
	global_store_dwordx4 v155, v[196:199], s[26:27] offset:16
	v_mul_f32_e32 v200, v181, v180
	v_add_u32_e32 v155, 0x200000, v201
	v_fma_f32 v188, -v200, v212, v213
	v_fma_f32 v189, -v200, v214, v215
	v_fma_f32 v190, -v200, v216, v217
	v_fma_f32 v191, -v200, v218, v219
	v_fma_f32 v192, -v200, v220, v221
	v_fma_f32 v193, -v200, v222, v223
	v_fma_f32 v194, -v200, v224, v225
	v_fma_f32 v195, -v200, v226, v227
	v_fma_f32 v62, v181, v62, v188
	v_fma_f32 v63, v181, v63, v189
; #define LAS __attribute__((address_space(3)))
; __device__ __forceinline__ float bf_lo(unsigned w) { return __uint_as_float(w << 16); }
;     __device__ __forceinline__ void operator()(const f32x4 (&acc)[2][2][4][2], const pg8::Unit& u, int wr, int wc, int fr, int fq, LAS unsigned char* lds, int par) const {
;         const bool fold = F.stats != nullptr;
;         const LAS float* rsb = (const LAS float*)(lds + RS_OFF) + par * 512; const LAS float* cvb = (const LAS float*)(lds + CV_OFF) + (par * 2 + wr) * 512;
;         const int row0 = u.pm * 256 + wr * 64 + fr, c0 = u.pn * 256 + wc * 64 + 16 * fq;
; #pragma unroll
;         for (int ai = 0; ai < 2; ++ai)
; #pragma unroll
;             for (int m = 0; m < 4; ++m) {
;                 const int row = row0 + ai * 128 + m * 16, lrow = ai * 128 + wr * 64 + m * 16 + fr;
;                 float mu = 0.f, rstd = 1.f; if (fold) { mu = rsb[2 * lrow]; rstd = rsb[2 * lrow + 1]; }
; #pragma unroll
;                 for (int bj = 0; bj < 2; ++bj) {
;                     const size_t off = (size_t)row * ld + c0 + bj * 8;
;                     f32x4 v0 = acc[ai][bj][m][0], v1 = acc[ai][bj][m][1];
;                     if (fold) fold_apply(v0, v1, mu, rstd, cvb, wc * 64 + 16 * fq + bj * 8);
;                     if (MODE == 0) { v0 *= scale; v1 *= scale; }
;                     if (MODE == 1) {
; #pragma unroll
;                         for (int j = 0; j < 4; ++j) { const float a = fmaxf(v0[j], 0.f), b = fmaxf(v1[j], 0.f); v0[j] = a * a; v1[j] = b * b; }
;                     }
;                     if (MODE == 2 || MODE == 3) {
;                         const u32x4 gw = *(const u32x4*)(gate + off);
;                         v0[0] *= bf_lo(gw.x); v0[1] *= bf_hi(gw.x); v0[2] *= bf_lo(gw.y); v0[3] *= bf_hi(gw.y);
;                         v1[0] *= bf_lo(gw.z); v1[1] *= bf_hi(gw.z); v1[2] *= bf_lo(gw.w); v1[3] *= bf_hi(gw.w);
;                     }
;                     if (MODE == 3) {
;                         const u32x4 pw = *(const u32x4*)(o + off);
;                         v0[0] += bf_lo(pw.x); v0[1] += bf_hi(pw.x); v0[2] += bf_lo(pw.y); v0[3] += bf_hi(pw.y);
;                         v1[0] += bf_lo(pw.z); v1[1] += bf_hi(pw.z); v1[2] += bf_lo(pw.w); v1[3] += bf_hi(pw.w);
;                     }
;                     *(u32x4*)(o + off) = pack8(v0, v1);
;                 }
	v_fma_f32 v64, v181, v64, v190
	v_fma_f32 v65, v181, v65, v191
	v_fma_f32 v58, v181, v58, v192
	v_fma_f32 v59, v181, v59, v193
	v_fma_f32 v60, v181, v60, v194
	v_fma_f32 v61, v181, v61, v195
	v_max_f32_e32 v62, 0, v62
	v_max_f32_e32 v63, 0, v63
	v_max_f32_e32 v64, 0, v64
	v_max_f32_e32 v65, 0, v65
	v_max_f32_e32 v58, 0, v58
	v_max_f32_e32 v59, 0, v59
	v_max_f32_e32 v60, 0, v60
	v_max_f32_e32 v61, 0, v61
	v_mul_f32_e32 v62, v62, v62
	v_mul_f32_e32 v63, v63, v63
	v_mul_f32_e32 v64, v64, v64
	v_mul_f32_e32 v65, v65, v65
	v_mul_f32_e32 v58, v58, v58
	v_mul_f32_e32 v59, v59, v59
	v_mul_f32_e32 v60, v60, v60
	v_mul_f32_e32 v61, v61, v61
	v_cvt_pk_bf16_f32 v196, v62, v63
	v_cvt_pk_bf16_f32 v197, v64, v65
	v_cvt_pk_bf16_f32 v198, v58, v59
	v_cvt_pk_bf16_f32 v199, v60, v61
	global_store_dwordx4 v155, v[196:199], s[26:27]
	v_fma_f32 v188, -v200, v228, v229
	v_fma_f32 v189, -v200, v230, v231
	v_fma_f32 v190, -v200, v232, v233
	v_fma_f32 v191, -v200, v234, v235
	v_fma_f32 v192, -v200, v236, v237
	v_fma_f32 v193, -v200, v238, v239
	v_fma_f32 v194, -v200, v240, v241
	v_fma_f32 v195, -v200, v242, v243
	v_fma_f32 v54, v181, v54, v188
	v_fma_f32 v55, v181, v55, v189
	v_fma_f32 v56, v181, v56, v190
	v_fma_f32 v57, v181, v57, v191
	v_fma_f32 v50, v181, v50, v192
	v_fma_f32 v51, v181, v51, v193
	v_fma_f32 v52, v181, v52, v194
	v_fma_f32 v53, v181, v53, v195
	v_max_f32_e32 v54, 0, v54
	v_max_f32_e32 v55, 0, v55
	v_max_f32_e32 v56, 0, v56
	v_max_f32_e32 v57, 0, v57
	v_max_f32_e32 v50, 0, v50
	v_max_f32_e32 v51, 0, v51
	v_max_f32_e32 v52, 0, v52
	v_max_f32_e32 v53, 0, v53
	v_mul_f32_e32 v54, v54, v54
	v_mul_f32_e32 v55, v55, v55
	v_mul_f32_e32 v56, v56, v56
	v_mul_f32_e32 v57, v57, v57
	v_mul_f32_e32 v50, v50, v50
	v_mul_f32_e32 v51, v51, v51
	v_mul_f32_e32 v52, v52, v52
	v_mul_f32_e32 v53, v53, v53
	v_cvt_pk_bf16_f32 v196, v54, v55
	v_cvt_pk_bf16_f32 v197, v56, v57
	v_cvt_pk_bf16_f32 v198, v50, v51
	v_cvt_pk_bf16_f32 v199, v52, v53
	global_store_dwordx4 v155, v[196:199], s[26:27] offset:16
	v_mul_f32_e32 v200, v183, v182
	v_add_u32_e32 v155, 0x240000, v201
	v_fma_f32 v188, -v200, v212, v213
	v_fma_f32 v189, -v200, v214, v215
	v_fma_f32 v190, -v200, v216, v217
	v_fma_f32 v191, -v200, v218, v219
	v_fma_f32 v192, -v200, v220, v221
	v_fma_f32 v193, -v200, v222, v223
	v_fma_f32 v194, -v200, v224, v225
	v_fma_f32 v195, -v200, v226, v227
	v_fma_f32 v46, v183, v46, v188
	v_fma_f32 v47, v183, v47, v189
	v_fma_f32 v48, v183, v48, v190
	v_fma_f32 v49, v183, v49, v191
	v_fma_f32 v42, v183, v42, v192
	v_fma_f32 v43, v183, v43, v193
	v_fma_f32 v44, v183, v44, v194
	v_fma_f32 v45, v183, v45, v195
	v_max_f32_e32 v46, 0, v46
	v_max_f32_e32 v47, 0, v47
	v_max_f32_e32 v48, 0, v48
	v_max_f32_e32 v49, 0, v49
	v_max_f32_e32 v42, 0, v42
	v_max_f32_e32 v43, 0, v43
	v_max_f32_e32 v44, 0, v44
	v_max_f32_e32 v45, 0, v45
	v_mul_f32_e32 v46, v46, v46
	v_mul_f32_e32 v47, v47, v47
	v_mul_f32_e32 v48, v48, v48
	v_mul_f32_e32 v49, v49, v49
	v_mul_f32_e32 v42, v42, v42
	v_mul_f32_e32 v43, v43, v43
	v_mul_f32_e32 v44, v44, v44
	v_mul_f32_e32 v45, v45, v45
	v_cvt_pk_bf16_f32 v196, v46, v47
	v_cvt_pk_bf16_f32 v197, v48, v49
	v_cvt_pk_bf16_f32 v198, v42, v43
	v_cvt_pk_bf16_f32 v199, v44, v45
	global_store_dwordx4 v155, v[196:199], s[26:27]
	v_fma_f32 v188, -v200, v228, v229
	v_fma_f32 v189, -v200, v230, v231
	v_fma_f32 v190, -v200, v232, v233
	v_fma_f32 v191, -v200, v234, v235
	v_fma_f32 v192, -v200, v236, v237
	v_fma_f32 v193, -v200, v238, v239
	v_fma_f32 v194, -v200, v240, v241
	v_fma_f32 v195, -v200, v242, v243
	v_fma_f32 v38, v183, v38, v188
	v_fma_f32 v39, v183, v39, v189
	v_fma_f32 v40, v183, v40, v190
	v_fma_f32 v41, v183, v41, v191
	v_fma_f32 v34, v183, v34, v192
	v_fma_f32 v35, v183, v35, v193
	v_fma_f32 v36, v183, v36, v194
	v_fma_f32 v37, v183, v37, v195
	v_max_f32_e32 v38, 0, v38
	v_max_f32_e32 v39, 0, v39
	v_max_f32_e32 v40, 0, v40
	v_max_f32_e32 v41, 0, v41
	v_max_f32_e32 v34, 0, v34
	v_max_f32_e32 v35, 0, v35
	v_max_f32_e32 v36, 0, v36
	v_max_f32_e32 v37, 0, v37
	v_mul_f32_e32 v38, v38, v38
	v_mul_f32_e32 v39, v39, v39
	v_mul_f32_e32 v40, v40, v40
	v_mul_f32_e32 v41, v41, v41
	v_mul_f32_e32 v34, v34, v34
	v_mul_f32_e32 v35, v35, v35
	v_mul_f32_e32 v36, v36, v36
	v_mul_f32_e32 v37, v37, v37
	v_cvt_pk_bf16_f32 v196, v38, v39
	v_cvt_pk_bf16_f32 v197, v40, v41
	v_cvt_pk_bf16_f32 v198, v34, v35
	v_cvt_pk_bf16_f32 v199, v36, v37
	global_store_dwordx4 v155, v[196:199], s[26:27] offset:16
	v_mul_f32_e32 v200, v185, v184
	v_add_u32_e32 v155, 0x280000, v201
	v_fma_f32 v188, -v200, v212, v213
	v_fma_f32 v189, -v200, v214, v215
	v_fma_f32 v190, -v200, v216, v217
	v_fma_f32 v191, -v200, v218, v219
	v_fma_f32 v192, -v200, v220, v221
	v_fma_f32 v193, -v200, v222, v223
	v_fma_f32 v194, -v200, v224, v225
	v_fma_f32 v195, -v200, v226, v227
	v_fma_f32 v30, v185, v30, v188
	v_fma_f32 v31, v185, v31, v189
	v_fma_f32 v32, v185, v32, v190
	v_fma_f32 v33, v185, v33, v191
	v_fma_f32 v26, v185, v26, v192
	v_fma_f32 v27, v185, v27, v193
	v_fma_f32 v28, v185, v28, v194
	v_fma_f32 v29, v185, v29, v195
	v_max_f32_e32 v30, 0, v30
	v_max_f32_e32 v31, 0, v31
	v_max_f32_e32 v32, 0, v32
	v_max_f32_e32 v33, 0, v33
	v_max_f32_e32 v26, 0, v26
	v_max_f32_e32 v27, 0, v27
	v_max_f32_e32 v28, 0, v28
	v_max_f32_e32 v29, 0, v29
	v_mul_f32_e32 v30, v30, v30
	v_mul_f32_e32 v31, v31, v31
	v_mul_f32_e32 v32, v32, v32
	v_mul_f32_e32 v33, v33, v33
	v_mul_f32_e32 v26, v26, v26
	v_mul_f32_e32 v27, v27, v27
	v_mul_f32_e32 v28, v28, v28
	v_mul_f32_e32 v29, v29, v29
	v_cvt_pk_bf16_f32 v196, v30, v31
	v_cvt_pk_bf16_f32 v197, v32, v33
	v_cvt_pk_bf16_f32 v198, v26, v27
	v_cvt_pk_bf16_f32 v199, v28, v29
;     __device__ __forceinline__ void prepare(const pg8::Unit& u, LAS unsigned char* lds, int par, int tid) const {
;         if (stats == nullptr) return;
;         const int h = tid >> 8, tt = tid & 255, rl = tt >> 1, part = tt & 1, lrow = (rl >> 6) * 128 + h * 64 + (rl & 63);
;         const float* sp = stats + ((size_t)(u.pm * 256 + lrow) * 32 + part * 16) * 2;
;     __device__ __forceinline__ void operator()(const f32x4 (&acc)[2][2][4][2], const pg8::Unit& u, int wr, int wc, int fr, int fq, LAS unsigned char* lds, int par) const {
;     ...
;         const int row0 = u.pm * 256 + wr * 64 + fr, c0 = u.pn * 256 + wc * 64 + 16 * fq;
; #pragma unroll
;         for (int ai = 0; ai < 2; ++ai)
; #pragma unroll
;             for (int m = 0; m < 4; ++m) {
;                 const int row = row0 + ai * 128 + m * 16, lrow = ai * 128 + wr * 64 + m * 16 + fr;
;                 float mu = 0.f, rstd = 1.f; if (fold) { mu = rsb[2 * lrow]; rstd = rsb[2 * lrow + 1]; }
; #pragma unroll
;                 for (int bj = 0; bj < 2; ++bj) {
;                     const size_t off = (size_t)row * ld + c0 + bj * 8;
;                     f32x4 v0 = acc[ai][bj][m][0], v1 = acc[ai][bj][m][1];
;                     if (fold) fold_apply(v0, v1, mu, rstd, cvb, wc * 64 + 16 * fq + bj * 8);
;                     if (MODE == 0) { v0 *= scale; v1 *= scale; }
;                     if (MODE == 1) {
; #pragma unroll
;                         for (int j = 0; j < 4; ++j) { const float a = fmaxf(v0[j], 0.f), b = fmaxf(v1[j], 0.f); v0[j] = a * a; v1[j] = b * b; }
;                     }
;                     if (MODE == 2 || MODE == 3) {
;                         const u32x4 gw = *(const u32x4*)(gate + off);
;                         v0[0] *= bf_lo(gw.x); v0[1] *= bf_hi(gw.x); v0[2] *= bf_lo(gw.y); v0[3] *= bf_hi(gw.y);
;                         v1[0] *= bf_lo(gw.z); v1[1] *= bf_hi(gw.z); v1[2] *= bf_lo(gw.w); v1[3] *= bf_hi(gw.w);
;                     }
;                     if (MODE == 3) {
;                         const u32x4 pw = *(const u32x4*)(o + off);
;                         v0[0] += bf_lo(pw.x); v0[1] += bf_hi(pw.x); v0[2] += bf_lo(pw.y); v0[3] += bf_hi(pw.y);
;                         v1[0] += bf_lo(pw.z); v1[1] += bf_hi(pw.z); v1[2] += bf_lo(pw.w); v1[3] += bf_hi(pw.w);
;                     }
;                     *(u32x4*)(o + off) = pack8(v0, v1);
;                 }
	global_store_dwordx4 v155, v[196:199], s[26:27]
	v_fma_f32 v188, -v200, v228, v229
	v_fma_f32 v189, -v200, v230, v231
	v_fma_f32 v190, -v200, v232, v233
	v_fma_f32 v191, -v200, v234, v235
	v_fma_f32 v192, -v200, v236, v237
	v_fma_f32 v193, -v200, v238, v239
	v_fma_f32 v194, -v200, v240, v241
	v_fma_f32 v195, -v200, v242, v243
	v_fma_f32 v22, v185, v22, v188
	v_fma_f32 v23, v185, v23, v189
	v_fma_f32 v24, v185, v24, v190
	v_fma_f32 v25, v185, v25, v191
	v_fma_f32 v18, v185, v18, v192
	v_fma_f32 v19, v185, v19, v193
	v_fma_f32 v20, v185, v20, v194
	v_fma_f32 v21, v185, v21, v195
	v_max_f32_e32 v22, 0, v22
	v_max_f32_e32 v23, 0, v23
	v_max_f32_e32 v24, 0, v24
	v_max_f32_e32 v25, 0, v25
	v_max_f32_e32 v18, 0, v18
	v_max_f32_e32 v19, 0, v19
	v_max_f32_e32 v20, 0, v20
	v_max_f32_e32 v21, 0, v21
	v_mul_f32_e32 v22, v22, v22
	v_mul_f32_e32 v23, v23, v23
	v_mul_f32_e32 v24, v24, v24
	v_mul_f32_e32 v25, v25, v25
	v_mul_f32_e32 v18, v18, v18
	v_mul_f32_e32 v19, v19, v19
	v_mul_f32_e32 v20, v20, v20
	v_mul_f32_e32 v21, v21, v21
	v_cvt_pk_bf16_f32 v196, v22, v23
	v_cvt_pk_bf16_f32 v197, v24, v25
	v_cvt_pk_bf16_f32 v198, v18, v19
	v_cvt_pk_bf16_f32 v199, v20, v21
	global_store_dwordx4 v155, v[196:199], s[26:27] offset:16
	v_mul_f32_e32 v200, v187, v186
	v_add_u32_e32 v155, 0x2c0000, v201
	v_fma_f32 v188, -v200, v212, v213
	v_fma_f32 v189, -v200, v214, v215
	v_fma_f32 v190, -v200, v216, v217
	v_fma_f32 v191, -v200, v218, v219
	v_fma_f32 v192, -v200, v220, v221
	v_fma_f32 v193, -v200, v222, v223
	v_fma_f32 v194, -v200, v224, v225
	v_fma_f32 v195, -v200, v226, v227
	v_fma_f32 v14, v187, v14, v188
	v_fma_f32 v15, v187, v15, v189
	v_fma_f32 v16, v187, v16, v190
	v_fma_f32 v17, v187, v17, v191
	v_fma_f32 v10, v187, v10, v192
	v_fma_f32 v11, v187, v11, v193
	v_fma_f32 v12, v187, v12, v194
	v_fma_f32 v13, v187, v13, v195
	v_max_f32_e32 v14, 0, v14
	v_max_f32_e32 v15, 0, v15
	v_max_f32_e32 v16, 0, v16
	v_max_f32_e32 v17, 0, v17
	v_max_f32_e32 v10, 0, v10
	v_max_f32_e32 v11, 0, v11
	v_max_f32_e32 v12, 0, v12
	v_max_f32_e32 v13, 0, v13
	v_mul_f32_e32 v14, v14, v14
	v_mul_f32_e32 v15, v15, v15
	v_mul_f32_e32 v16, v16, v16
	v_mul_f32_e32 v17, v17, v17
	v_mul_f32_e32 v10, v10, v10
	v_mul_f32_e32 v11, v11, v11
	v_mul_f32_e32 v12, v12, v12
	v_mul_f32_e32 v13, v13, v13
	v_cvt_pk_bf16_f32 v196, v14, v15
	v_cvt_pk_bf16_f32 v197, v16, v17
	v_cvt_pk_bf16_f32 v198, v10, v11
	v_cvt_pk_bf16_f32 v199, v12, v13
	global_store_dwordx4 v155, v[196:199], s[26:27]
	v_fma_f32 v188, -v200, v228, v229
	v_fma_f32 v189, -v200, v230, v231
	v_fma_f32 v190, -v200, v232, v233
	v_fma_f32 v191, -v200, v234, v235
	v_fma_f32 v192, -v200, v236, v237
	v_fma_f32 v193, -v200, v238, v239
	v_fma_f32 v194, -v200, v240, v241
	v_fma_f32 v195, -v200, v242, v243
	v_fma_f32 v6, v187, v6, v188
	v_fma_f32 v7, v187, v7, v189
	v_fma_f32 v8, v187, v8, v190
	v_fma_f32 v9, v187, v9, v191
	v_fma_f32 v2, v187, v2, v192
	v_fma_f32 v3, v187, v3, v193
	v_fma_f32 v4, v187, v4, v194
	v_fma_f32 v5, v187, v5, v195
	v_max_f32_e32 v6, 0, v6
	v_max_f32_e32 v7, 0, v7
	v_max_f32_e32 v8, 0, v8
	v_max_f32_e32 v9, 0, v9
	v_max_f32_e32 v2, 0, v2
	v_max_f32_e32 v3, 0, v3
	v_max_f32_e32 v4, 0, v4
	v_max_f32_e32 v5, 0, v5
	v_mul_f32_e32 v6, v6, v6
	v_mul_f32_e32 v7, v7, v7
	v_mul_f32_e32 v8, v8, v8
	v_mul_f32_e32 v9, v9, v9
	v_mul_f32_e32 v2, v2, v2
	v_mul_f32_e32 v3, v3, v3
	v_mul_f32_e32 v4, v4, v4
	v_mul_f32_e32 v5, v5, v5
	v_cvt_pk_bf16_f32 v196, v6, v7
	v_cvt_pk_bf16_f32 v197, v8, v9
	v_cvt_pk_bf16_f32 v198, v2, v3
	v_cvt_pk_bf16_f32 v199, v4, v5
	global_store_dwordx4 v155, v[196:199], s[26:27] offset:16
	s_andn2_b64 vcc, exec, s[22:23]
	s_mov_b64 s[22:23], -1
	s_cbranch_vccnz .LBB0_164
	s_nop 0
	v_lshl_add_u32 v2, s16, 8, v144
	v_ashrrev_i32_e32 v3, 31, v2
	v_lshlrev_b64 v[2:3], 8, v[2:3]
	v_lshl_add_u64 v[6:7], v[136:137], 0, v[2:3]
	global_load_dwordx4 v[2:5], v[6:7], off
	global_load_dwordx4 v[222:225], v[6:7], off offset:16
	global_load_dwordx4 v[226:229], v[6:7], off offset:32
	global_load_dwordx4 v[230:233], v[6:7], off offset:48
	global_load_dwordx4 v[234:237], v[6:7], off offset:64
	global_load_dwordx4 v[238:241], v[6:7], off offset:80
	global_load_dwordx4 v[242:245], v[6:7], off offset:96
	global_load_dwordx4 v[246:249], v[6:7], off offset:112
	s_and_b32 s15, s39, 1
	s_waitcnt vmcnt(0) lgkmcnt(0)
	v_add_f32_e32 v2, v2, v4
	v_add_f32_e32 v8, 0, v2
	v_add_f32_e32 v2, v3, v5
	v_add_f32_e32 v9, 0, v2
	v_add_f32_e32 v2, v222, v224
	v_add_f32_e32 v8, v8, v2
	v_add_f32_e32 v2, v223, v225
	v_add_f32_e32 v9, v9, v2
	v_add_f32_e32 v2, v226, v228
	v_add_f32_e32 v8, v8, v2
	v_add_f32_e32 v2, v227, v229
	v_add_f32_e32 v9, v9, v2
	v_add_f32_e32 v2, v230, v232
	v_add_f32_e32 v8, v8, v2
	v_add_f32_e32 v2, v231, v233
	v_add_f32_e32 v9, v9, v2
	v_add_f32_e32 v2, v234, v236
	v_add_f32_e32 v8, v8, v2
	v_add_f32_e32 v2, v235, v237
	v_add_f32_e32 v9, v9, v2
	v_add_f32_e32 v2, v238, v240
	v_add_f32_e32 v8, v8, v2
	v_add_f32_e32 v2, v239, v241
	v_add_f32_e32 v9, v9, v2
	v_add_f32_e32 v2, v242, v244
	v_add_f32_e32 v8, v8, v2
	v_add_f32_e32 v2, v243, v245
	v_add_f32_e32 v9, v9, v2
	v_add_f32_e32 v2, v246, v248
	v_add_f32_e32 v3, v247, v249
	v_add_f32_e32 v2, v8, v2
	v_add_f32_e32 v3, v9, v3
	ds_bpermute_b32 v4, v145, v2
	ds_bpermute_b32 v5, v145, v3
	s_and_saveexec_b64 s[22:23], s[0:1]
	s_cbranch_execz .LBB0_179
	s_waitcnt lgkmcnt(1)
	v_add_f32_e32 v2, v2, v4
	v_mul_f32_e32 v2, 0x3a000000, v2
	s_waitcnt lgkmcnt(0)
	v_add_f32_e32 v3, v3, v5
	v_mul_f32_e32 v4, v2, v2
	v_fma_f32 v3, v3, s61, -v4
	v_add_f32_e32 v3, 0x3727c5ac, v3
	v_rsq_f32_e32 v3, v3
	v_lshl_add_u32 v4, s15, 11, v151
	ds_write_b64 v4, v[2:3]
